# ffn gate/up GEMM K-loop body hand-rescheduled on top of the MLA work: two full LDS fragment sets (next k-substep reads always in flight behind 8 MFMAs), counted lgkmcnt
# speedup vs baseline: 1.0117x; 1.0026x over previous
; #define RAW_BARRIER() do { asm volatile("s_waitcnt lgkmcnt(0)" ::: "memory"); __builtin_amdgcn_s_barrier(); } while (0)
;   DI u16* kt() const { return (u16*)(ws + O_KT); }
; template <class DescFn, class EpiFn>
; DI void gemm_stream(unsigned char* smem, const int wv, const int start, const int stride, const int end, const int ldb, const int nk, DescFn&& desc, EpiFn&& mkepi) {
;     ...
;   int cur_i = start;
;   TileDesc cur = desc(cur_i);
;   DMA(cur, 0, 0);
; #pragma unroll 1
;   while (true) {
;     const int nxt_i = cur_i + stride;
;     const bool has_next = nxt_i < end;
;     TileDesc nxt = cur;
;     if (has_next) nxt = desc(nxt_i);
;     f32x16 acc[2][4];
; #pragma unroll
;     for (int a = 0; a < 2; ++a)
; #pragma unroll
;       for (int b = 0; b < 4; ++b) zero_acc(acc[a][b]);
;     bf16x8 Fw0, Fw1, Ft0, Ft1, Ft2, Ft3, Gw0, Gw1, Gt0, Gt1, Gt2, Gt3;
; #pragma unroll 1
;     for (int kt = 0; kt < nk; ++kt) {
;       const int buf = kt & 1;
;       asm volatile("s_waitcnt vmcnt(0)" ::: "memory");
;       RAW_BARRIER();
;       if (wave < 4) {
;         if (kt + 1 < nk) { DMA(cur, kt + 1, buf ^ 1); }
;         else if (has_next) { DMA(nxt, 0, 0); }
;       }
.LBB0_181:
	v_lshl_add_u64 v[0:1], s[6:7], 0, v[152:153]
	v_mov_b32_e32 v159, v165
	v_lshl_add_u64 v[2:3], s[8:9], 0, v[152:153]
	v_lshl_add_u64 v[162:163], v[0:1], 0, v[164:165]
	v_lshl_add_u64 v[0:1], v[0:1], 0, v[158:159]
	s_mov_b64 s[18:19], 0x4000
	s_mov_b64 s[24:25], 0xc000
	s_mov_b64 s[28:29], 0x14000
	s_mov_b64 s[34:35], 0x1c000
	v_lshl_add_u64 v[168:169], v[0:1], 0, s[18:19]
	v_lshl_add_u64 v[172:173], v[0:1], 0, s[24:25]
	v_lshl_add_u64 v[176:177], v[0:1], 0, s[28:29]
	v_lshl_add_u64 v[180:181], v[0:1], 0, s[34:35]
	v_lshl_add_u64 v[0:1], v[2:3], 0, v[158:159]
	s_mov_b64 s[22:23], 0x8000
	s_mov_b64 s[26:27], 0x10000
	s_mov_b64 s[30:31], 0x18000
	v_lshl_add_u64 v[182:183], v[2:3], 0, v[164:165]
	v_lshl_add_u64 v[184:185], v[0:1], 0, s[18:19]
	v_lshl_add_u64 v[188:189], v[0:1], 0, s[24:25]
	v_lshl_add_u64 v[192:193], v[0:1], 0, s[28:29]
	v_lshl_add_u64 v[196:197], v[0:1], 0, s[34:35]
	v_mov_b32_e32 v0, 0
	v_lshl_add_u64 v[170:171], v[162:163], 0, s[22:23]
	v_lshl_add_u64 v[174:175], v[162:163], 0, s[26:27]
	v_lshl_add_u64 v[178:179], v[162:163], 0, s[30:31]
	v_lshl_add_u64 v[186:187], v[182:183], 0, s[22:23]
	v_lshl_add_u64 v[190:191], v[182:183], 0, s[26:27]
	v_lshl_add_u64 v[194:195], v[182:183], 0, s[30:31]
	v_lshl_add_u64 v[198:199], s[12:13], 0, v[154:155]
	v_lshl_add_u64 v[200:201], s[12:13], 0, v[156:157]
	v_lshl_add_u64 v[202:203], s[10:11], 0, v[156:157]
	v_lshl_add_u64 v[204:205], s[10:11], 0, v[154:155]
	s_mov_b32 s18, 0
	s_mov_b64 s[10:11], 0
	v_mov_b32_e32 v1, v0
	v_mov_b32_e32 v2, v0
	v_mov_b32_e32 v3, v0
	v_mov_b32_e32 v4, v0
	v_mov_b32_e32 v5, v0
	v_mov_b32_e32 v6, v0
	v_mov_b32_e32 v7, v0
	v_mov_b32_e32 v8, v0
	v_mov_b32_e32 v9, v0
	v_mov_b32_e32 v10, v0
	v_mov_b32_e32 v11, v0
	v_mov_b32_e32 v12, v0
	v_mov_b32_e32 v13, v0
	v_mov_b32_e32 v14, v0
	v_mov_b32_e32 v15, v0
	v_mov_b32_e32 v16, v0
	v_mov_b32_e32 v17, v0
	v_mov_b32_e32 v18, v0
	v_mov_b32_e32 v19, v0
	v_mov_b32_e32 v20, v0
	v_mov_b32_e32 v21, v0
	v_mov_b32_e32 v22, v0
	v_mov_b32_e32 v23, v0
	v_mov_b32_e32 v24, v0
	v_mov_b32_e32 v25, v0
	v_mov_b32_e32 v26, v0
	v_mov_b32_e32 v27, v0
	v_mov_b32_e32 v28, v0
	v_mov_b32_e32 v29, v0
	v_mov_b32_e32 v30, v0
	v_mov_b32_e32 v31, v0
	v_mov_b32_e32 v32, v0
	v_mov_b32_e32 v33, v0
	v_mov_b32_e32 v34, v0
	v_mov_b32_e32 v35, v0
	v_mov_b32_e32 v36, v0
	v_mov_b32_e32 v37, v0
	v_mov_b32_e32 v38, v0
	v_mov_b32_e32 v39, v0
	v_mov_b32_e32 v40, v0
	v_mov_b32_e32 v41, v0
	v_mov_b32_e32 v42, v0
	v_mov_b32_e32 v43, v0
	v_mov_b32_e32 v44, v0
	v_mov_b32_e32 v45, v0
	v_mov_b32_e32 v46, v0
	v_mov_b32_e32 v47, v0
	v_mov_b32_e32 v48, v0
	v_mov_b32_e32 v49, v0
	v_mov_b32_e32 v50, v0
	v_mov_b32_e32 v51, v0
	v_mov_b32_e32 v52, v0
	v_mov_b32_e32 v53, v0
	v_mov_b32_e32 v54, v0
	v_mov_b32_e32 v55, v0
	v_mov_b32_e32 v56, v0
	v_mov_b32_e32 v57, v0
	v_mov_b32_e32 v58, v0
	v_mov_b32_e32 v59, v0
	v_mov_b32_e32 v60, v0
	v_mov_b32_e32 v61, v0
	v_mov_b32_e32 v62, v0
	v_mov_b32_e32 v63, v0
	v_mov_b32_e32 v64, v0
	v_mov_b32_e32 v65, v0
	v_mov_b32_e32 v66, v0
	v_mov_b32_e32 v67, v0
	v_mov_b32_e32 v68, v0
	v_mov_b32_e32 v69, v0
	v_mov_b32_e32 v70, v0
	v_mov_b32_e32 v71, v0
	v_mov_b32_e32 v72, v0
	v_mov_b32_e32 v73, v0
	v_mov_b32_e32 v74, v0
	v_mov_b32_e32 v75, v0
	v_mov_b32_e32 v76, v0
	v_mov_b32_e32 v77, v0
	v_mov_b32_e32 v78, v0
	v_mov_b32_e32 v79, v0
	v_mov_b32_e32 v80, v0
	v_mov_b32_e32 v81, v0
	v_mov_b32_e32 v82, v0
	v_mov_b32_e32 v83, v0
	v_mov_b32_e32 v84, v0
	v_mov_b32_e32 v85, v0
	v_mov_b32_e32 v86, v0
	v_mov_b32_e32 v87, v0
	v_mov_b32_e32 v88, v0
	v_mov_b32_e32 v89, v0
	v_mov_b32_e32 v90, v0
	v_mov_b32_e32 v91, v0
	v_mov_b32_e32 v92, v0
	v_mov_b32_e32 v93, v0
	v_mov_b32_e32 v94, v0
	v_mov_b32_e32 v95, v0
	v_mov_b32_e32 v96, v0
	v_mov_b32_e32 v97, v0
	v_mov_b32_e32 v98, v0
	v_mov_b32_e32 v99, v0
	v_mov_b32_e32 v100, v0
	v_mov_b32_e32 v101, v0
	v_mov_b32_e32 v102, v0
	v_mov_b32_e32 v103, v0
	v_mov_b32_e32 v104, v0
	v_mov_b32_e32 v105, v0
	v_mov_b32_e32 v106, v0
	v_mov_b32_e32 v107, v0
	v_mov_b32_e32 v108, v0
	v_mov_b32_e32 v109, v0
	v_mov_b32_e32 v110, v0
	v_mov_b32_e32 v111, v0
	v_mov_b32_e32 v112, v0
	v_mov_b32_e32 v113, v0
	v_mov_b32_e32 v114, v0
	v_mov_b32_e32 v115, v0
	v_mov_b32_e32 v116, v0
	v_mov_b32_e32 v117, v0
	v_mov_b32_e32 v118, v0
	v_mov_b32_e32 v119, v0
	v_mov_b32_e32 v120, v0
	v_mov_b32_e32 v121, v0
	v_mov_b32_e32 v122, v0
	v_mov_b32_e32 v123, v0
	v_mov_b32_e32 v124, v0
	v_mov_b32_e32 v125, v0
	v_mov_b32_e32 v126, v0
	v_mov_b32_e32 v127, v0
	s_branch .LBB0_183
.LBB0_183:
	s_waitcnt vmcnt(0)
	s_waitcnt lgkmcnt(0)
	s_and_b32 s19, s18, 1
	s_andn2_b64 vcc, exec, s[40:41]
	s_barrier
	s_cbranch_vccnz .LBB0_189
	s_cmpk_eq_i32 s10, 0x780
	s_mov_b64 s[12:13], -1
	s_cbranch_scc1 .LBB0_186
	s_lshl_b32 s12, s19, 16
	s_xor_b32 s12, s12, 0x10000
	s_or_b32 s12, s50, s12
	v_lshl_add_u64 v[128:129], v[204:205], 0, s[10:11]
	v_lshl_add_u64 v[130:131], v[128:129], 0, s[44:45]
	s_mov_b32 m0, s12
	s_mov_b64 s[22:23], 0x4080
	global_load_lds_dwordx4 v[130:131], off
	v_lshl_add_u64 v[130:131], v[202:203], 0, s[10:11]
	v_lshl_add_u64 v[132:133], v[130:131], 0, s[22:23]
	s_add_i32 m0, s12, 0x400
	s_mov_b64 s[22:23], 0x8080
	global_load_lds_dwordx4 v[132:133], off
	v_lshl_add_u64 v[132:133], v[128:129], 0, s[22:23]
	s_add_i32 m0, s12, 0x800
	s_mov_b64 s[22:23], 0xc080
	global_load_lds_dwordx4 v[132:133], off
	v_lshl_add_u64 v[132:133], v[130:131], 0, s[22:23]
	s_add_i32 m0, s12, 0xc00
	s_mov_b64 s[22:23], 0x10080
	global_load_lds_dwordx4 v[132:133], off
	v_lshl_add_u64 v[132:133], v[128:129], 0, s[22:23]
	s_add_i32 m0, s12, 0x1000
	s_mov_b64 s[22:23], 0x14080
	global_load_lds_dwordx4 v[132:133], off
	v_lshl_add_u64 v[132:133], v[130:131], 0, s[22:23]
	s_add_i32 m0, s12, 0x1400
	s_mov_b64 s[22:23], 0x18080
	global_load_lds_dwordx4 v[132:133], off
	v_lshl_add_u64 v[128:129], v[128:129], 0, s[22:23]
	s_add_i32 m0, s12, 0x1800
	s_mov_b64 s[22:23], 0x1c080
	global_load_lds_dwordx4 v[128:129], off
	v_lshl_add_u64 v[128:129], v[130:131], 0, s[22:23]
	s_add_i32 m0, s12, 0x1c00
	s_mov_b64 s[12:13], 0
	global_load_lds_dwordx4 v[128:129], off

;   DI u16* kt() const { return (u16*)(ws + O_KT); }
; template <class DescFn, class EpiFn>
; DI void gemm_stream(unsigned char* smem, const int wv, const int start, const int stride, const int end, const int ldb, const int nk, DescFn&& desc, EpiFn&& mkepi) {
;     ...
;       const unsigned char* sbase = smem + buf * 65536;
;       LOADF(0, F);
;       LOADF(1, G);
;       MMA(F);
;       if (wave >= 4) {
;         if (kt + 1 < nk) { DMA(cur, kt + 1, buf ^ 1); }
;         else if (has_next) { DMA(nxt, 0, 0); }
;       }
;       MMA(G);
.LBB0_189:
	s_lshl_b32 s19, s19, 16
	s_add_i32 s12, s19, s51
	v_add_u32_e32 v159, s12, v206
	s_or_b32 s12, s19, s49
	v_add_u32_e32 v161, s12, v206
	v_add_u32_e32 v236, v159, v207
	v_add_u32_e32 v237, v161, v207
	ds_read_b128 v[128:131], v236 offset:32768
	ds_read_b128 v[132:135], v236 offset:36864
	ds_read_b128 v[136:139], v237
	ds_read_b128 v[140:143], v237 offset:4096
	ds_read_b128 v[144:147], v237 offset:8192
	ds_read_b128 v[148:151], v237 offset:12288
	v_add_u32_e32 v236, v159, v208
	v_add_u32_e32 v237, v161, v208
	ds_read_b128 v[212:215], v236 offset:32768
	ds_read_b128 v[216:219], v236 offset:36864
	ds_read_b128 v[220:223], v237
	ds_read_b128 v[224:227], v237 offset:4096
	ds_read_b128 v[228:231], v237 offset:8192
	ds_read_b128 v[232:235], v237 offset:12288
	s_waitcnt lgkmcnt(6)
	v_mfma_f32_32x32x16_bf16 v[112:127], v[128:131], v[136:139], v[112:127]
	v_mfma_f32_32x32x16_bf16 v[96:111], v[132:135], v[136:139], v[96:111]
	v_mfma_f32_32x32x16_bf16 v[80:95], v[128:131], v[140:143], v[80:95]
	v_mfma_f32_32x32x16_bf16 v[64:79], v[132:135], v[140:143], v[64:79]
	v_mfma_f32_32x32x16_bf16 v[48:63], v[128:131], v[144:147], v[48:63]
	v_mfma_f32_32x32x16_bf16 v[32:47], v[132:135], v[144:147], v[32:47]
	v_mfma_f32_32x32x16_bf16 v[16:31], v[128:131], v[148:151], v[16:31]
	v_mfma_f32_32x32x16_bf16 v[0:15], v[132:135], v[148:151], v[0:15]
	v_add_u32_e32 v236, v159, v209
	v_add_u32_e32 v237, v161, v209
	ds_read_b128 v[128:131], v236 offset:32768
	ds_read_b128 v[132:135], v236 offset:36864
	ds_read_b128 v[136:139], v237
	ds_read_b128 v[140:143], v237 offset:4096
	ds_read_b128 v[144:147], v237 offset:8192
	ds_read_b128 v[148:151], v237 offset:12288
	v_readlane_b32 s12, v251, 57
	v_readlane_b32 s13, v251, 58
	s_andn2_b64 vcc, exec, s[12:13]
	s_cbranch_vccnz .Lf1_second
	s_cmpk_eq_i32 s10, 0x780
	s_mov_b64 s[12:13], -1
	s_cbranch_scc1 .LBB0_192
	s_xor_b32 s12, s19, 0x10000
	s_add_i32 s12, s50, s12
	v_lshl_add_u64 v[166:167], v[198:199], 0, s[10:11]
	v_lshl_add_u64 v[242:243], v[166:167], 0, s[44:45]
	s_mov_b32 m0, s12
	s_mov_b64 s[22:23], 0x4080
	global_load_lds_dwordx4 v[242:243], off
	v_lshl_add_u64 v[242:243], v[200:201], 0, s[10:11]
	v_lshl_add_u64 v[244:245], v[242:243], 0, s[22:23]
	s_add_i32 m0, s12, 0x400
	s_mov_b64 s[22:23], 0x8080
	global_load_lds_dwordx4 v[244:245], off
	v_lshl_add_u64 v[244:245], v[166:167], 0, s[22:23]
	s_add_i32 m0, s12, 0x800
	s_mov_b64 s[22:23], 0xc080
	global_load_lds_dwordx4 v[244:245], off
	v_lshl_add_u64 v[244:245], v[242:243], 0, s[22:23]
	s_add_i32 m0, s12, 0xc00
	s_mov_b64 s[22:23], 0x10080
	global_load_lds_dwordx4 v[244:245], off
	v_lshl_add_u64 v[244:245], v[166:167], 0, s[22:23]
	s_add_i32 m0, s12, 0x1000
	s_mov_b64 s[22:23], 0x14080
	global_load_lds_dwordx4 v[244:245], off
	v_lshl_add_u64 v[244:245], v[242:243], 0, s[22:23]
	s_add_i32 m0, s12, 0x1400
	s_mov_b64 s[22:23], 0x18080
	global_load_lds_dwordx4 v[244:245], off
	v_lshl_add_u64 v[166:167], v[166:167], 0, s[22:23]
	s_add_i32 m0, s12, 0x1800
	s_mov_b64 s[22:23], 0x1c080
	global_load_lds_dwordx4 v[166:167], off
	v_lshl_add_u64 v[166:167], v[242:243], 0, s[22:23]
	s_add_i32 m0, s12, 0x1c00
	s_mov_b64 s[12:13], 0
	global_load_lds_dwordx4 v[166:167], off

; template <class DescFn, class EpiFn>
; DI void gemm_stream(unsigned char* smem, const int wv, const int start, const int stride, const int end, const int ldb, const int nk, DescFn&& desc, EpiFn&& mkepi) {
;     ...
;       MMA(G);
;       LOADF(2, F);
;       LOADF(3, G);
;       MMA(F);
;       MMA(G);
;     }
.Lf1_second:
	s_waitcnt lgkmcnt(6)
	v_mfma_f32_32x32x16_bf16 v[112:127], v[212:215], v[220:223], v[112:127]
	v_mfma_f32_32x32x16_bf16 v[96:111], v[216:219], v[220:223], v[96:111]
	v_mfma_f32_32x32x16_bf16 v[80:95], v[212:215], v[224:227], v[80:95]
	v_mfma_f32_32x32x16_bf16 v[64:79], v[216:219], v[224:227], v[64:79]
	v_mfma_f32_32x32x16_bf16 v[48:63], v[212:215], v[228:231], v[48:63]
	v_mfma_f32_32x32x16_bf16 v[32:47], v[216:219], v[228:231], v[32:47]
	v_mfma_f32_32x32x16_bf16 v[16:31], v[212:215], v[232:235], v[16:31]
	v_mfma_f32_32x32x16_bf16 v[0:15], v[216:219], v[232:235], v[0:15]
	v_add_u32_e32 v236, v159, v210
	v_add_u32_e32 v237, v161, v210
	ds_read_b128 v[212:215], v236 offset:32768
	ds_read_b128 v[216:219], v236 offset:36864
	ds_read_b128 v[220:223], v237
	ds_read_b128 v[224:227], v237 offset:4096
	ds_read_b128 v[228:231], v237 offset:8192
	ds_read_b128 v[232:235], v237 offset:12288
	s_waitcnt lgkmcnt(6)
	v_mfma_f32_32x32x16_bf16 v[112:127], v[128:131], v[136:139], v[112:127]
	v_mfma_f32_32x32x16_bf16 v[96:111], v[132:135], v[136:139], v[96:111]
	v_mfma_f32_32x32x16_bf16 v[80:95], v[128:131], v[140:143], v[80:95]
	v_mfma_f32_32x32x16_bf16 v[64:79], v[132:135], v[140:143], v[64:79]
	v_mfma_f32_32x32x16_bf16 v[48:63], v[128:131], v[144:147], v[48:63]
	v_mfma_f32_32x32x16_bf16 v[32:47], v[132:135], v[144:147], v[32:47]
	v_mfma_f32_32x32x16_bf16 v[16:31], v[128:131], v[148:151], v[16:31]
	v_mfma_f32_32x32x16_bf16 v[0:15], v[132:135], v[148:151], v[0:15]
	s_waitcnt lgkmcnt(0)
	v_mfma_f32_32x32x16_bf16 v[112:127], v[212:215], v[220:223], v[112:127]
	v_mfma_f32_32x32x16_bf16 v[96:111], v[216:219], v[220:223], v[96:111]
	v_mfma_f32_32x32x16_bf16 v[80:95], v[212:215], v[224:227], v[80:95]
	v_mfma_f32_32x32x16_bf16 v[64:79], v[216:219], v[224:227], v[64:79]
	v_mfma_f32_32x32x16_bf16 v[48:63], v[212:215], v[228:231], v[48:63]
	v_mfma_f32_32x32x16_bf16 v[32:47], v[216:219], v[228:231], v[32:47]
	v_mfma_f32_32x32x16_bf16 v[16:31], v[212:215], v[232:235], v[16:31]
	v_mfma_f32_32x32x16_bf16 v[0:15], v[216:219], v[232:235], v[0:15]
	s_add_i32 s18, s18, 1
	s_add_u32 s10, s10, 0x80
	s_addc_u32 s11, s11, 0
	s_cmpk_eq_i32 s10, 0x800
	s_cbranch_scc1 .LBB0_178
	s_branch .LBB0_183
